# attention epilogue: SiLU-gate fragments prefetched before the key-tile walk, norm-weight fragments loaded together, counted waits
# speedup vs baseline: 1.0453x; 1.0033x over previous
; #define BLK_BAR() asm volatile("s_waitcnt lgkmcnt(0)\n\ts_barrier" ::: "memory")
; DI void fox_attn_blk(const Params& P, unsigned char* lds, LAS unsigned char* ldsl, int tid, int G, float PRUNE, int pir) {
;     ...
;         if (lane == 0) nvs[wave] = nvalid;
;         BLK_BAR();
;         int nvmax = 0;
; #pragma unroll
;         for (int w_ = 0; w_ < 8; ++w_) { const int v_ = nvs[w_]; nvmax = v_ > nvmax ? v_ : nvmax; }
;         nvmax = __builtin_amdgcn_readfirstlane(nvmax);
;         if (nvmax >= 56) {
;             BLK_BAR();
;             fox_attn_unit(P, tid, h, qb, PRUNE, pir);
;             continue; }
;     ...
;         for (int j_ = 0; j_ < 11; ++j_) DMA_TILE(QB0 + 7 - j_);
;     ...
;             for (int gi = 0; gi < 4; ++gi) { const int d = 32 * blk + 8 * gi + 4 * hi;
;                 const u32x2 z = *(const u32x2*)(FZ + rowoff + d); const f32x4 w = *(const f32x4*)(P.in[11] + d);
.LBB0_740:
	s_or_b64 exec, exec, s[0:1]
	s_cmp_lg_u32 s60, -1
	s_cselect_b32 s0, s60, 0
	v_lshlrev_b64 v[194:195], 9, v[2:3]
	s_cselect_b32 s1, s61, 0
	v_mov_b32_e32 v2, s0
	s_add_i32 s0, 0, 0x1e004
	s_cmp_lg_u32 s0, -1
	s_waitcnt lgkmcnt(0)
	s_barrier
	v_mov_b32_e32 v3, s1
	s_cselect_b32 s0, s0, 0
	flat_load_dword v4, v[2:3] sc0 sc1
	s_waitcnt vmcnt(0)
	s_cselect_b32 s1, s61, 0
	v_mov_b32_e32 v2, s0
	s_add_i32 s0, 0, 0x1e008
	s_cmp_lg_u32 s0, -1
	v_mov_b32_e32 v3, s1
	s_cselect_b32 s0, s0, 0
	s_cselect_b32 s1, s61, 0
	flat_load_dword v5, v[2:3] sc0 sc1
	s_waitcnt vmcnt(0)
	v_mov_b32_e32 v2, s0
	v_mov_b32_e32 v3, s1
	flat_load_dword v2, v[2:3] sc0 sc1
	s_waitcnt vmcnt(0)
	s_add_i32 s0, 0, 0x1e00c
	s_cmp_lg_u32 s0, -1
	s_cselect_b32 s0, s0, 0
	s_cselect_b32 s1, s61, 0
	v_mov_b32_e32 v3, s1
	v_or_b32_e32 v194, s9, v194
	s_waitcnt lgkmcnt(0)
	v_max3_i32 v4, v4, v5, v2
	v_mov_b32_e32 v2, s0
	s_add_i32 s0, 0, 0x1e010
	s_cmp_lg_u32 s0, -1
	s_cselect_b32 s0, s0, 0
	s_cselect_b32 s1, s61, 0
	flat_load_dword v5, v[2:3] sc0 sc1
	s_waitcnt vmcnt(0)
	v_mov_b32_e32 v2, s0
	v_mov_b32_e32 v3, s1
	flat_load_dword v2, v[2:3] sc0 sc1
	s_waitcnt vmcnt(0)
	s_add_i32 s0, 0, 0x1e014
	s_cmp_lg_u32 s0, -1
	s_cselect_b32 s0, s0, 0
	s_cselect_b32 s1, s61, 0
	v_mov_b32_e32 v3, s1
	s_waitcnt lgkmcnt(0)
	v_max3_i32 v4, v4, v5, v2
	v_mov_b32_e32 v2, s0
	s_add_i32 s0, 0, 0x1e018
	s_cmp_lg_u32 s0, -1
	s_cselect_b32 s0, s0, 0
	s_cselect_b32 s1, s61, 0
	flat_load_dword v5, v[2:3] sc0 sc1
	s_waitcnt vmcnt(0)
	v_mov_b32_e32 v2, s0
	v_mov_b32_e32 v3, s1
	flat_load_dword v2, v[2:3] sc0 sc1
	s_waitcnt vmcnt(0)
	s_add_i32 s0, 0, 0x1e01c
	s_cmp_lg_u32 s0, -1
	s_cselect_b32 s0, s0, 0
	s_cselect_b32 s1, s61, 0
	v_mov_b32_e32 v3, s1
	s_waitcnt lgkmcnt(0)
	v_max3_i32 v4, v4, v5, v2
	v_mov_b32_e32 v2, s0
	flat_load_dword v2, v[2:3] sc0 sc1
	s_waitcnt vmcnt(0)
	s_mov_b64 s[0:1], -1
	s_waitcnt lgkmcnt(0)
	v_max3_i32 v2, v4, v2, 0
	s_nop 0
	v_readfirstlane_b32 s5, v2
	s_cmp_gt_i32 s5, 55
	s_cbranch_scc1 .LBB0_765
	v_lshlrev_b64 v[254:255], 1, v[194:195]
	v_lshl_add_u64 v[254:255], v[186:187], 0, v[254:255]
	global_load_dwordx2 v[240:241], v[254:255], off
	global_load_dwordx2 v[242:243], v[254:255], off offset:16
	global_load_dwordx2 v[244:245], v[254:255], off offset:32
	global_load_dwordx2 v[246:247], v[254:255], off offset:48
	global_load_dwordx2 v[248:249], v[254:255], off offset:64
	global_load_dwordx2 v[250:251], v[254:255], off offset:80
	global_load_dwordx2 v[252:253], v[254:255], off offset:96
	global_load_dwordx2 v[254:255], v[254:255], off offset:112
	s_or_b32 s0, s33, 7
	s_max_i32 s2, s0, 0
	s_add_i32 s0, s33, 0x7f
	s_mul_hi_i32 s1, s0, 0x2aaaaaab
	s_lshr_b32 s56, s1, 31
	s_lshr_b32 s1, s1, 1
	s_add_i32 s1, s1, s56
	s_mul_i32 s1, s1, 12
	s_sub_i32 s56, s0, s1
	v_mad_u64_u32 v[2:3], s[0:1], v168, s2, 0
	s_mulk_i32 s56, 0x2800
	s_add_i32 s0, s56, 0
	v_lshl_add_u64 v[2:3], v[2:3], 1, v[172:173]
	s_add_i32 m0, s0, s84
	s_add_i32 s0, s0, s85
	global_load_lds_dwordx4 v[2:3], off
	s_add_i32 m0, s0, 0x2000
	s_or_b32 s0, s33, 6
	s_lshl_b32 s62, s2, 5
	s_max_i32 s2, s0, 0
	s_add_i32 s0, s33, 0x7e
	s_mul_hi_i32 s1, s0, 0x2aaaaaab
	s_lshr_b32 s56, s1, 31
	s_lshr_b32 s1, s1, 1
	s_add_i32 s1, s1, s56
	s_mul_i32 s1, s1, 12
	v_lshl_add_u64 v[2:3], s[62:63], 2, v[166:167]
	s_sub_i32 s56, s0, s1
	global_load_lds_dword v[2:3], off
	v_mad_u64_u32 v[2:3], s[0:1], v168, s2, 0
	s_mulk_i32 s56, 0x2800
	s_add_i32 s0, s56, 0
	v_lshl_add_u64 v[2:3], v[2:3], 1, v[172:173]
	s_add_i32 m0, s0, s84
	s_add_i32 s0, s0, s85
	global_load_lds_dwordx4 v[2:3], off
	s_add_i32 m0, s0, 0x2000
	s_or_b32 s0, s33, 5
	s_lshl_b32 s62, s2, 5
	s_max_i32 s2, s0, 0
	s_add_i32 s0, s33, 0x7d
	s_mul_hi_i32 s1, s0, 0x2aaaaaab
	s_lshr_b32 s56, s1, 31
	s_lshr_b32 s1, s1, 1
	s_add_i32 s1, s1, s56
	s_mul_i32 s1, s1, 12
	v_lshl_add_u64 v[2:3], s[62:63], 2, v[166:167]
	s_sub_i32 s56, s0, s1
	global_load_lds_dword v[2:3], off
	v_mad_u64_u32 v[2:3], s[0:1], v168, s2, 0
	s_mulk_i32 s56, 0x2800
	s_add_i32 s0, s56, 0
	v_lshl_add_u64 v[2:3], v[2:3], 1, v[172:173]
	s_add_i32 m0, s0, s84
	s_add_i32 s0, s0, s85
	global_load_lds_dwordx4 v[2:3], off
	s_add_i32 m0, s0, 0x2000
	s_or_b32 s0, s33, 4
	s_lshl_b32 s62, s2, 5
	s_max_i32 s2, s0, 0
	s_add_i32 s0, s33, 0x7c
	s_mul_hi_i32 s1, s0, 0x2aaaaaab
	s_lshr_b32 s56, s1, 31
	s_lshr_b32 s1, s1, 1
	s_add_i32 s1, s1, s56
	s_mul_i32 s1, s1, 12
	v_lshl_add_u64 v[2:3], s[62:63], 2, v[166:167]
	s_sub_i32 s56, s0, s1
	global_load_lds_dword v[2:3], off
	v_mad_u64_u32 v[2:3], s[0:1], v168, s2, 0
	s_mulk_i32 s56, 0x2800
	s_add_i32 s0, s56, 0
	v_lshl_add_u64 v[2:3], v[2:3], 1, v[172:173]
	s_add_i32 m0, s0, s84
	s_add_i32 s0, s0, s85
	global_load_lds_dwordx4 v[2:3], off
	s_add_i32 m0, s0, 0x2000
	s_or_b32 s0, s33, 3
	s_lshl_b32 s62, s2, 5
	s_max_i32 s2, s0, 0
	s_add_i32 s0, s33, 0x7b
	s_mul_hi_i32 s1, s0, 0x2aaaaaab
	s_lshr_b32 s56, s1, 31
	s_lshr_b32 s1, s1, 1
	s_add_i32 s1, s1, s56
	s_mul_i32 s1, s1, 12
	v_lshl_add_u64 v[2:3], s[62:63], 2, v[166:167]
	s_sub_i32 s56, s0, s1
	global_load_lds_dword v[2:3], off
	v_mad_u64_u32 v[2:3], s[0:1], v168, s2, 0
	s_mulk_i32 s56, 0x2800
	s_add_i32 s0, s56, 0
	v_lshl_add_u64 v[2:3], v[2:3], 1, v[172:173]
	s_add_i32 m0, s0, s84
	s_add_i32 s0, s0, s85
	global_load_lds_dwordx4 v[2:3], off
	s_add_i32 m0, s0, 0x2000
	s_or_b32 s0, s33, 2
	s_lshl_b32 s62, s2, 5
	s_max_i32 s2, s0, 0
	s_add_i32 s0, s33, 0x7a
	s_mul_hi_i32 s1, s0, 0x2aaaaaab
	s_lshr_b32 s56, s1, 31
	s_lshr_b32 s1, s1, 1
	s_add_i32 s1, s1, s56
	s_mul_i32 s1, s1, 12
	v_lshl_add_u64 v[2:3], s[62:63], 2, v[166:167]
	s_sub_i32 s56, s0, s1
	global_load_lds_dword v[2:3], off
	v_mad_u64_u32 v[2:3], s[0:1], v168, s2, 0
; #define BLK_BAR() asm volatile("s_waitcnt lgkmcnt(0)\n\ts_barrier" ::: "memory")
; DI void fox_attn_blk(const Params& P, unsigned char* lds, LAS unsigned char* ldsl, int tid, int G, float PRUNE, int pir) {
;     ...
;         for (int j_ = 0; j_ < 11; ++j_) DMA_TILE(QB0 + 7 - j_);
;         asm volatile("s_waitcnt vmcnt(6)" ::: "memory");
;         float mrun = -INFINITY, lsum = 0.f;
;         f32x16 oT[2];
; #pragma unroll
;         for (int i = 0; i < 16; ++i) { oT[0][i] = 0.f; oT[1][i] = 0.f; }
;         BLK_BAR();
;         const bool stag = wvu >= 4; bool pend = false;
;         f32x16 sc; bf16x8 vf[2][2]; float alpha = 1.f;
; #pragma unroll
;         for (int i = 0; i < 16; ++i) sc[i] = 0.f;
;         vf[0][0] = vf[0][1] = vf[1][0] = vf[1][1] = (bf16x8){0, 0, 0, 0, 0, 0, 0, 0};
;     ...
;         for (int it = 0; it <= nvmax; ++it) {
	s_mulk_i32 s56, 0x2800
	s_add_i32 s0, s56, 0
	v_lshl_add_u64 v[2:3], v[2:3], 1, v[172:173]
	s_add_i32 m0, s0, s84
	s_add_i32 s0, s0, s85
	global_load_lds_dwordx4 v[2:3], off
	s_add_i32 m0, s0, 0x2000
	s_or_b32 s0, s33, 1
	s_lshl_b32 s62, s2, 5
	s_max_i32 s2, s0, 0
	s_add_i32 s0, s33, 0x79
	s_mul_hi_i32 s1, s0, 0x2aaaaaab
	s_lshr_b32 s56, s1, 31
	s_lshr_b32 s1, s1, 1
	s_add_i32 s1, s1, s56
	s_mul_i32 s1, s1, 12
	v_lshl_add_u64 v[2:3], s[62:63], 2, v[166:167]
	s_sub_i32 s56, s0, s1
	global_load_lds_dword v[2:3], off
	v_mad_u64_u32 v[2:3], s[0:1], v168, s2, 0
	s_mulk_i32 s56, 0x2800
	s_add_i32 s0, s56, 0
	v_lshl_add_u64 v[2:3], v[2:3], 1, v[172:173]
	s_add_i32 m0, s0, s84
	s_add_i32 s0, s0, s85
	global_load_lds_dwordx4 v[2:3], off
	s_add_i32 m0, s0, 0x2000
	s_add_i32 s0, s33, 0x78
	s_mul_hi_i32 s1, s0, 0x2aaaaaab
	s_lshr_b32 s56, s1, 31
	s_lshr_b32 s1, s1, 1
	s_add_i32 s1, s1, s56
	s_lshl_b32 s62, s2, 5
	s_mul_i32 s1, s1, 12
	v_lshl_add_u64 v[2:3], s[62:63], 2, v[166:167]
	s_max_i32 s2, s33, 0
	s_sub_i32 s56, s0, s1
	global_load_lds_dword v[2:3], off
	v_mad_u64_u32 v[2:3], s[0:1], v168, s2, 0
	s_mulk_i32 s56, 0x2800
	s_add_i32 s0, s56, 0
	v_lshl_add_u64 v[2:3], v[2:3], 1, v[172:173]
	s_add_i32 m0, s0, s84
	s_add_i32 s0, s0, s85
	global_load_lds_dwordx4 v[2:3], off
	s_add_i32 m0, s0, 0x2000
	s_max_i32 s0, s33, 1
	s_lshl_b32 s62, s2, 5
	s_add_i32 s2, s0, -1
	s_add_i32 s0, s33, 0x77
	s_mul_hi_i32 s1, s0, 0x2aaaaaab
	s_lshr_b32 s56, s1, 31
	s_lshr_b32 s1, s1, 1
	s_add_i32 s1, s1, s56
	s_mul_i32 s1, s1, 12
	v_lshl_add_u64 v[2:3], s[62:63], 2, v[166:167]
	s_sub_i32 s56, s0, s1
	global_load_lds_dword v[2:3], off
	v_mad_u64_u32 v[2:3], s[0:1], v168, s2, 0
	s_mulk_i32 s56, 0x2800
	s_add_i32 s0, s56, 0
	v_lshl_add_u64 v[2:3], v[2:3], 1, v[172:173]
	s_add_i32 m0, s0, s84
	s_add_i32 s0, s0, s85
	global_load_lds_dwordx4 v[2:3], off
	s_add_i32 m0, s0, 0x2000
	s_max_i32 s0, s33, 2
	s_lshl_b32 s62, s2, 5
	s_add_i32 s2, s0, -2
	s_add_i32 s0, s33, 0x76
	s_mul_hi_i32 s1, s0, 0x2aaaaaab
	s_lshr_b32 s56, s1, 31
	s_lshr_b32 s1, s1, 1
	s_add_i32 s1, s1, s56
	s_mul_i32 s1, s1, 12
	v_lshl_add_u64 v[2:3], s[62:63], 2, v[166:167]
	s_sub_i32 s56, s0, s1
	global_load_lds_dword v[2:3], off
	v_mad_u64_u32 v[2:3], s[0:1], v168, s2, 0
	s_mulk_i32 s56, 0x2800
	s_add_i32 s0, s56, 0
	v_lshl_add_u64 v[2:3], v[2:3], 1, v[172:173]
	s_add_i32 m0, s0, s84
	s_add_i32 s0, s0, s85
	global_load_lds_dwordx4 v[2:3], off
	s_add_i32 m0, s0, 0x2000
	s_max_i32 s0, s33, 3
	s_lshl_b32 s62, s2, 5
	s_add_i32 s2, s0, -3
	s_add_i32 s0, s33, 0x75
	s_mul_hi_i32 s1, s0, 0x2aaaaaab
	s_lshr_b32 s56, s1, 31
	s_lshr_b32 s1, s1, 1
	s_add_i32 s1, s1, s56
	s_mul_i32 s1, s1, 12
	v_lshl_add_u64 v[2:3], s[62:63], 2, v[166:167]
	s_sub_i32 s56, s0, s1
	global_load_lds_dword v[2:3], off
	v_mad_u64_u32 v[2:3], s[0:1], v168, s2, 0
	s_mulk_i32 s56, 0x2800
	s_add_i32 s0, s56, 0
	v_lshl_add_u64 v[2:3], v[2:3], 1, v[172:173]
	s_add_i32 m0, s0, s84
	s_lshl_b32 s62, s2, 5
	s_add_i32 s0, s0, s85
	global_load_lds_dwordx4 v[2:3], off
	v_lshl_add_u64 v[2:3], s[62:63], 2, v[166:167]
	s_add_i32 m0, s0, 0x2000
	s_cmp_gt_i32 s5, -1
	global_load_lds_dword v[2:3], off
	s_waitcnt vmcnt(6)
	s_waitcnt lgkmcnt(0)
	s_barrier
	s_cbranch_scc0 .LBB0_744
; #define MFMA32(a, b, c) __builtin_amdgcn_mfma_f32_32x32x16_bf16((a), (b), (c), 0, 0, 0)
; DI void fox_attn_blk(const Params& P, unsigned char* lds, LAS unsigned char* ldsl, int tid, int G, float PRUNE, int pir) {
;     ...
;         for (int it = 0; it <= nvmax; ++it) {
;             if (pend) { ATT_TAIL(); pend = false; }
;             DMA_TILE(QB0 - it - 4);
;             const int kt = qb - it;
;             if (it <= nvalid) {
;                 const unsigned char* tb = lds + ((kt + 120) % 12) * 10240;
;                 const float off = it == 0 ? 0.f : __int_as_float(__builtin_amdgcn_readlane(__float_as_int(offv), it - 1));
;                 bf16x8 kf[4]; f32x4 ck[4];
; #pragma unroll
;                 for (int ks = 0; ks < 4; ++ks) kf[ks] = *(const bf16x8*)(tb + koff + (((2 * ks + hi) ^ ksw) << 4));
; #pragma unroll
;                 for (int blk = 0; blk < 2; ++blk)
; #pragma unroll
;                     for (int s = 0; s < 2; ++s) vf[blk][s] = *(const bf16x8*)(tb + voff + blk * 2048 + (((2 * s + hi) ^ vsw) << 4));
; #pragma unroll
;                 for (int s = 0; s < 2; ++s) { ck[2 * s] = *(const f32x4*)(tb + 8192 + wvu * 256 + (16 * s + 8 * hi) * 4); ck[2 * s + 1] = *(const f32x4*)(tb + 8192 + wvu * 256 + (16 * s + 8 * hi) * 4 + 16); }
;                 const float cb = cq + off;
; #pragma unroll
;                 for (int i = 0; i < 16; ++i) sc[i] = cb;
; #pragma unroll
;                 for (int ks = 0; ks < 4; ++ks) sc = MFMA32(kf[ks], qf[ks], sc);
;                 float mx = -INFINITY;
; #pragma unroll
;                 for (int r = 0; r < 16; ++r) { const int kl = 16 * (r >> 3) + 8 * hi + (r & 7);
;                     float v = sc[r] - ck[r >> 2][r & 3];
;                     if (kt == qb && kl > r32) v = -INFINITY;
;                     sc[r] = v; mx = fmaxf(mx, v); }
;                 { const auto rr = __builtin_amdgcn_permlane32_swap(__float_as_uint(mx), __float_as_uint(mx), false, false);
;                   mx = fmaxf(__uint_as_float(rr[0]), __uint_as_float(rr[1])); }
;                 const float mnew = fmaxf(mrun, mx); alpha = __builtin_amdgcn_exp2f(mrun - mnew); mrun = mnew;
; #pragma unroll
;                 for (int r = 0; r < 16; ++r) sc[r] = __builtin_amdgcn_exp2f(sc[r] - mnew);
;                 if (stag) pend = true; else ATT_TAIL();
	s_max_i32 s0, s33, 4
	s_addk_i32 s33, 0x74
	s_add_i32 s2, s0, -4
	s_mul_hi_i32 s0, s33, 0x2aaaaaab
	s_lshr_b32 s1, s0, 31
	s_lshr_b32 s0, s0, 1
	s_add_i32 s0, s0, s1
	s_mul_i32 s0, s0, 12
	s_sub_i32 s33, s33, s0
	v_mad_u64_u32 v[2:3], s[0:1], v168, s2, 0
	s_mulk_i32 s33, 0x2800
	s_add_i32 s0, s33, 0
	v_lshl_add_u64 v[2:3], v[2:3], 1, v[172:173]
	s_add_i32 m0, s0, s84
	s_lshl_b32 s62, s2, 5
	s_add_i32 s0, s0, s85
	global_load_lds_dwordx4 v[2:3], off
	v_lshl_add_u64 v[2:3], s[62:63], 2, v[166:167]
	s_add_i32 m0, s0, 0x2000
	v_add_u32_e32 v4, 0x78, v88
	global_load_lds_dword v[2:3], off
	v_mul_hi_i32 v2, v4, s89
	v_lshrrev_b32_e32 v3, 31, v2
	v_lshrrev_b32_e32 v2, 1, v2
	v_add_u32_e32 v2, v2, v3
	v_mul_lo_u32 v2, v2, 12
	v_sub_u32_e32 v2, v4, v2
	v_mad_i32_i24 v26, v2, s90, 0
	v_add_u32_e32 v27, v26, v169
	v_add_u32_e32 v2, v27, v214
	v_add_u32_e32 v3, v27, v215
	ds_read_b128 v[18:21], v2
	ds_read_b128 v[22:25], v3
	v_add_f32_e32 v2, 0, v90
	v_mov_b32_e32 v3, v2
	v_mov_b32_e32 v4, v2
	v_mov_b32_e32 v5, v2
	v_mov_b32_e32 v6, v2
	v_mov_b32_e32 v7, v2
	v_mov_b32_e32 v8, v2
	v_mov_b32_e32 v9, v2
	v_mov_b32_e32 v10, v2
	v_mov_b32_e32 v11, v2
	v_mov_b32_e32 v12, v2
	v_mov_b32_e32 v13, v2
	v_mov_b32_e32 v14, v2
	v_mov_b32_e32 v15, v2
	v_mov_b32_e32 v16, v2
	v_mov_b32_e32 v17, v2
	v_add3_u32 v34, v26, s85, v207
	s_andn2_b64 vcc, exec, s[38:39]
	s_waitcnt lgkmcnt(0)
	v_mfma_f32_32x32x16_bf16 v[2:17], v[18:21], v[50:53], v[2:17]
	v_add_u32_e32 v18, v27, v216
	ds_read_b128 v[18:21], v18
	v_mfma_f32_32x32x16_bf16 v[2:17], v[22:25], v[54:57], v[2:17]
	v_add_u32_e32 v22, v27, v217
	ds_read_b128 v[22:25], v22
	v_add_u32_e32 v27, v26, v196
	v_add_u32_e32 v28, v27, v218
	v_add_u32_e32 v27, v27, v219
	ds_read_b128 v[74:77], v28 offset:4096
	ds_read_b128 v[70:73], v28 offset:6144
	ds_read_b128 v[78:81], v27 offset:4096
	ds_read_b128 v[66:69], v27 offset:6144
	s_waitcnt lgkmcnt(0)
	v_mfma_f32_32x32x16_bf16 v[2:17], v[18:21], v[58:61], v[2:17]
	ds_read_b128 v[18:21], v34 offset:8192
	ds_read_b128 v[26:29], v34 offset:8208
	ds_read_b128 v[30:33], v34 offset:8256
	ds_read_b128 v[34:37], v34 offset:8272
	v_mfma_f32_32x32x16_bf16 v[2:17], v[22:25], v[62:65], v[2:17]
	s_waitcnt lgkmcnt(0)
	s_nop 10
	v_sub_f32_e32 v2, v2, v18
	v_sub_f32_e32 v3, v3, v19
	v_cndmask_b32_e64 v2, v2, v223, s[40:41]
	v_cndmask_b32_e64 v3, v223, v3, s[42:43]
	v_sub_f32_e32 v4, v4, v20
	v_sub_f32_e32 v5, v5, v21
	v_max3_f32 v18, v2, s88, v3
	v_cndmask_b32_e64 v4, v4, v223, s[44:45]
	v_cndmask_b32_e64 v5, v5, v223, s[26:27]
	v_sub_f32_e32 v6, v6, v26
	v_sub_f32_e32 v7, v7, v27
	v_max3_f32 v18, v18, v4, v5
	v_cndmask_b32_e64 v6, v6, v223, s[28:29]
	v_cndmask_b32_e64 v7, v7, v223, s[30:31]
	v_sub_f32_e32 v8, v8, v28
	v_sub_f32_e32 v9, v9, v29
	v_max3_f32 v18, v18, v6, v7
	v_cndmask_b32_e64 v8, v8, v223, s[34:35]
	v_cndmask_b32_e64 v9, v9, v223, s[74:75]
	v_sub_f32_e32 v10, v10, v30
	v_sub_f32_e32 v11, v11, v31
	v_max3_f32 v18, v18, v8, v9
	v_cndmask_b32_e64 v10, v10, v223, s[76:77]
	v_cndmask_b32_e64 v11, v11, v223, s[82:83]
	v_sub_f32_e32 v12, v12, v32
	v_sub_f32_e32 v13, v13, v33
	v_max3_f32 v18, v18, v10, v11
	v_cndmask_b32_e64 v12, v12, v223, s[70:71]
	v_cndmask_b32_e64 v13, v13, v223, s[78:79]
	v_sub_f32_e32 v14, v14, v34
	v_sub_f32_e32 v15, v15, v35
	v_max3_f32 v18, v18, v12, v13
	v_cndmask_b32_e64 v14, v14, v223, s[20:21]
	v_cndmask_b32_e64 v15, v15, v223, s[22:23]
	v_sub_f32_e32 v16, v16, v36
	v_sub_f32_e32 v17, v17, v37
	v_max3_f32 v18, v18, v14, v15
	v_cndmask_b32_e64 v16, v16, v223, s[24:25]
	v_cndmask_b32_e64 v17, v17, v223, s[52:53]
	v_max3_f32 v18, v18, v16, v17
	v_mov_b32_e32 v19, v18
	s_nop 1
	v_permlane32_swap_b32_e32 v18, v19
	v_max3_f32 v94, v18, v19, s88
	v_sub_f32_e32 v2, v2, v94
	v_exp_f32_e32 v92, v2
	v_sub_f32_e32 v2, v3, v94
	v_exp_f32_e32 v37, v2
	v_sub_f32_e32 v2, v4, v94
	v_exp_f32_e32 v40, v2
	v_sub_f32_e32 v2, v5, v94
	v_exp_f32_e32 v44, v2
	v_sub_f32_e32 v2, v6, v94
	v_exp_f32_e32 v38, v2
	v_sub_f32_e32 v2, v7, v94
	v_exp_f32_e32 v41, v2
	v_sub_f32_e32 v2, v8, v94
	v_exp_f32_e32 v45, v2
	v_sub_f32_e32 v2, v9, v94
	v_exp_f32_e32 v46, v2
	v_sub_f32_e32 v2, v10, v94
	v_exp_f32_e32 v47, v2
	v_sub_f32_e32 v2, v11, v94
	v_exp_f32_e32 v48, v2
	v_sub_f32_e32 v2, v12, v94
	v_exp_f32_e32 v49, v2
	v_sub_f32_e32 v2, v13, v94
	v_exp_f32_e32 v35, v2
	v_sub_f32_e32 v2, v14, v94
	v_exp_f32_e32 v36, v2
	v_sub_f32_e32 v2, v15, v94
	v_exp_f32_e32 v39, v2
	v_sub_f32_e32 v2, v16, v94
	v_sub_f32_e32 v18, 0xff800000, v94
	v_exp_f32_e32 v42, v2
	v_sub_f32_e32 v2, v17, v94
	v_exp_f32_e32 v43, v2
	v_exp_f32_e32 v34, v18
	v_cndmask_b32_e64 v2, 0, 1, s[38:39]
	v_cmp_ne_u32_e64 s[56:57], 1, v2
	s_cbranch_vccnz .LBB0_745
	v_add_f32_e32 v2, 0, v92
	v_add_f32_e32 v2, v37, v2
	v_add_f32_e32 v2, v40, v2
	v_add_f32_e32 v2, v44, v2
	v_add_f32_e32 v2, v38, v2
	v_add_f32_e32 v2, v41, v2
	v_add_f32_e32 v2, v45, v2
	v_add_f32_e32 v2, v46, v2
	v_add_f32_e32 v2, v47, v2
	v_add_f32_e32 v2, v48, v2
	v_add_f32_e32 v2, v49, v2
	v_add_f32_e32 v2, v35, v2
	v_add_f32_e32 v2, v36, v2
	v_add_f32_e32 v2, v39, v2
	v_cmp_neq_f32_e32 vcc, 1.0, v34
	v_add_f32_e32 v2, v42, v2
	s_cmp_lg_u64 vcc, 0
	v_add_f32_e32 v93, v43, v2
	v_mul_f32_e32 v2, 0, v34
	s_cselect_b64 vcc, -1, 0
	v_cndmask_b32_e32 v2, 0, v2, vcc
	v_cvt_pk_bf16_f32 v96, v92, v37
	v_cvt_pk_bf16_f32 v97, v40, v44
	v_cvt_pk_bf16_f32 v98, v38, v41
	v_cvt_pk_bf16_f32 v99, v45, v46
	v_mov_b32_e32 v3, v2
	v_mov_b32_e32 v4, v2
	v_mov_b32_e32 v5, v2
	v_mov_b32_e32 v6, v2
	v_mov_b32_e32 v7, v2
	v_mov_b32_e32 v8, v2
	v_mov_b32_e32 v9, v2
	v_mov_b32_e32 v10, v2
	v_mov_b32_e32 v11, v2
	v_mov_b32_e32 v12, v2
	v_mov_b32_e32 v13, v2
	v_mov_b32_e32 v14, v2
	v_mov_b32_e32 v15, v2
	v_mov_b32_e32 v16, v2
	v_mov_b32_e32 v17, v2
	v_cvt_pk_bf16_f32 v100, v47, v48
	v_cvt_pk_bf16_f32 v101, v49, v35
	v_mfma_f32_32x32x16_bf16 v[18:33], v[74:77], v[96:99], v[2:17]
	v_cvt_pk_bf16_f32 v102, v36, v39
	v_cvt_pk_bf16_f32 v103, v42, v43
	v_fmac_f32_e32 v93, 0, v34
	v_mfma_f32_32x32x16_bf16 v[2:17], v[70:73], v[96:99], v[2:17]
	v_mfma_f32_32x32x16_bf16 v[18:33], v[78:81], v[100:103], v[18:33]
	v_mfma_f32_32x32x16_bf16 v[2:17], v[66:69], v[100:103], v[2:17]
	s_branch .LBB0_746

; __device__ __forceinline__ float bflo(unsigned u) { return __uint_as_float(u << 16); }
; __device__ __forceinline__ float bfhi(unsigned u) { return __uint_as_float(u & 0xffff0000u); }
; DI float bflo(unsigned u) { return __uint_as_float(u << 16); }
; DI float bfhi(unsigned u) { return __uint_as_float(u & 0xffff0000u); }
; DI unsigned pk2(float lo, float hi) { f32x2_t v = {lo, hi}; bf16x2_t b = __builtin_convertvector(v, bf16x2_t); return __builtin_bit_cast(unsigned, b); }
; DI float sigmf(float v) { return __builtin_amdgcn_rcpf(1.0f + __expf(-v)); }
; DI void fox_attn_blk(const Params& P, unsigned char* lds, LAS unsigned char* ldsl, int tid, int G, float PRUNE, int pir) {
;     ...
;         { const auto rr = __builtin_amdgcn_permlane32_swap(__float_as_uint(lsum), __float_as_uint(lsum), false, false); lsum = __uint_as_float(rr[0]) + __uint_as_float(rr[1]); }
;         const float inv = 1.0f / lsum;
;         float ss = 0.f;
; #pragma unroll
;         for (int i = 0; i < 16; ++i) { oT[0][i] *= inv; oT[1][i] *= inv; ss += oT[0][i] * oT[0][i] + oT[1][i] * oT[1][i]; }
;         { const auto rr = __builtin_amdgcn_permlane32_swap(__float_as_uint(ss), __float_as_uint(ss), false, false); ss = __uint_as_float(rr[0]) + __uint_as_float(rr[1]); }
;         const float rstd = rsqrtf(ss * (1.f / 64.f) + EPS);
; #pragma unroll
;         for (int blk = 0; blk < 2; ++blk)
; #pragma unroll
;             for (int gi = 0; gi < 4; ++gi) { const int d = 32 * blk + 8 * gi + 4 * hi;
;                 const u32x2 z = *(const u32x2*)(FZ + rowoff + d); const f32x4 w = *(const f32x4*)(P.in[11] + d);
;                 const float z0 = bflo(z.x), z1 = bfhi(z.x), z2 = bflo(z.y), z3 = bfhi(z.y);
;                 u32x2 o; o.x = pk2(oT[blk][4 * gi] * rstd * w.x * z0 * sigmf(z0), oT[blk][4 * gi + 1] * rstd * w.y * z1 * sigmf(z1));
;                 o.y = pk2(oT[blk][4 * gi + 2] * rstd * w.z * z2 * sigmf(z2), oT[blk][4 * gi + 3] * rstd * w.w * z3 * sigmf(z3));
;                 *(u32x2*)(YB + rowoff + d) = o; }
.LBB0_764:
	v_lshlrev_b64 v[34:35], 1, v[194:195]
	v_lshl_add_u64 v[36:37], v[186:187], 0, v[34:35]
	v_mov_b32_e32 v50, v240
	v_mov_b32_e32 v51, v241
	v_mov_b32_e32 v40, v242
	v_mov_b32_e32 v41, v243
	global_load_dwordx4 v[64:67], v[178:179], off
	global_load_dwordx4 v[68:71], v[178:179], off offset:32
	global_load_dwordx4 v[72:75], v[178:179], off offset:64
	global_load_dwordx4 v[76:79], v[178:179], off offset:96
	global_load_dwordx4 v[80:83], v[178:179], off offset:128
	global_load_dwordx4 v[84:87], v[178:179], off offset:160
	global_load_dwordx4 v[88:91], v[178:179], off offset:192
	global_load_dwordx4 v[96:99], v[178:179], off offset:224
	v_mov_b32_e32 v38, v93
	s_nop 1
	v_permlane32_swap_b32_e32 v93, v38
	v_add_f32_e32 v38, v93, v38
	v_div_scale_f32 v39, s[0:1], v38, v38, 1.0
	v_rcp_f32_e32 v42, v39
	v_div_scale_f32 v43, vcc, 1.0, v38, 1.0
	v_lshl_add_u64 v[34:35], v[188:189], 0, v[34:35]
	v_fma_f32 v44, -v39, v42, 1.0
	v_fmac_f32_e32 v42, v44, v42
	v_mul_f32_e32 v44, v43, v42
	v_fma_f32 v45, -v39, v44, v43
	v_fmac_f32_e32 v44, v45, v42
	v_fma_f32 v39, -v39, v44, v43
	v_div_fmas_f32 v39, v39, v42, v44
	v_div_fixup_f32 v52, v39, v38, 1.0
	v_pk_mul_f32 v[42:43], v[24:25], v[52:53] op_sel_hi:[1,0]
	v_pk_mul_f32 v[24:25], v[2:3], v[52:53] op_sel_hi:[1,0]
	v_pk_mul_f32 v[56:57], v[18:19], v[52:53] op_sel_hi:[1,0]
	v_pk_mul_f32 v[44:45], v[22:23], v[52:53] op_sel_hi:[1,0]
	v_pk_mul_f32 v[22:23], v[4:5], v[52:53] op_sel_hi:[1,0]
	v_pk_mul_f32 v[18:19], v[8:9], v[52:53] op_sel_hi:[1,0]
	v_pk_mul_f32 v[8:9], v[12:13], v[52:53] op_sel_hi:[1,0]
	v_pk_mul_f32 v[12:13], v[10:11], v[52:53] op_sel_hi:[1,0]
	v_pk_mul_f32 v[10:11], v[24:25], v[24:25]
	v_pk_mul_f32 v[54:55], v[20:21], v[52:53] op_sel_hi:[1,0]
	v_pk_mul_f32 v[4:5], v[22:23], v[22:23]
	v_pk_fma_f32 v[10:11], v[56:57], v[56:57], v[10:11]
	v_pk_mul_f32 v[20:21], v[6:7], v[52:53] op_sel_hi:[1,0]
	v_pk_fma_f32 v[4:5], v[54:55], v[54:55], v[4:5]
	v_pk_add_f32 v[10:11], v[10:11], v[10:11] op_sel:[0,1] op_sel_hi:[1,0]
	v_pk_mul_f32 v[38:39], v[26:27], v[52:53] op_sel_hi:[1,0]
	v_pk_mul_f32 v[26:27], v[30:31], v[52:53] op_sel_hi:[1,0]
	v_pk_mul_f32 v[30:31], v[20:21], v[20:21]
	v_pk_add_f32 v[10:11], v[4:5], v[10:11]
	v_pk_fma_f32 v[30:31], v[44:45], v[44:45], v[30:31]
	v_pk_add_f32 v[4:5], v[4:5], v[10:11] op_sel:[1,0] op_sel_hi:[0,1]
	v_pk_mul_f32 v[6:7], v[14:15], v[52:53] op_sel_hi:[1,0]
	v_pk_mul_f32 v[14:15], v[18:19], v[18:19]
	v_pk_add_f32 v[4:5], v[30:31], v[4:5]
	v_pk_fma_f32 v[14:15], v[42:43], v[42:43], v[14:15]
	v_pk_add_f32 v[4:5], v[30:31], v[4:5] op_sel:[1,0] op_sel_hi:[0,1]
	v_pk_mul_f32 v[58:59], v[12:13], v[12:13]
	v_pk_add_f32 v[4:5], v[14:15], v[4:5]
	v_pk_fma_f32 v[58:59], v[38:39], v[38:39], v[58:59]
	v_pk_add_f32 v[4:5], v[14:15], v[4:5] op_sel:[1,0] op_sel_hi:[0,1]
	v_pk_mul_f32 v[32:33], v[32:33], v[52:53] op_sel_hi:[1,0]
	v_pk_mul_f32 v[16:17], v[16:17], v[52:53] op_sel_hi:[1,0]
	v_pk_mul_f32 v[28:29], v[28:29], v[52:53] op_sel_hi:[1,0]
	v_pk_mul_f32 v[52:53], v[8:9], v[8:9]
	v_pk_add_f32 v[4:5], v[58:59], v[4:5]
	v_pk_fma_f32 v[52:53], v[28:29], v[28:29], v[52:53]
	v_pk_add_f32 v[4:5], v[58:59], v[4:5] op_sel:[1,0] op_sel_hi:[0,1]
	v_pk_mul_f32 v[60:61], v[6:7], v[6:7]
	v_pk_add_f32 v[4:5], v[52:53], v[4:5]
	v_pk_fma_f32 v[60:61], v[26:27], v[26:27], v[60:61]
	v_pk_add_f32 v[4:5], v[52:53], v[4:5] op_sel:[1,0] op_sel_hi:[0,1]
	v_pk_mul_f32 v[2:3], v[16:17], v[16:17]
	v_pk_add_f32 v[4:5], v[60:61], v[4:5]
	v_pk_fma_f32 v[2:3], v[32:33], v[32:33], v[2:3]
	v_pk_add_f32 v[4:5], v[60:61], v[4:5] op_sel:[1,0] op_sel_hi:[0,1]
	v_pk_add_f32 v[4:5], v[2:3], v[4:5]
	s_mov_b64 s[0:1], 0
	v_pk_add_f32 v[2:3], v[2:3], v[4:5] op_sel:[1,0] op_sel_hi:[0,1]
	v_mov_b32_e32 v3, v2
	s_nop 1
	v_permlane32_swap_b32_e32 v2, v3
	v_add_f32_e32 v2, v2, v3
	v_fmamk_f32 v2, v2, 0x3c800000, v222
	v_mul_f32_e32 v3, 0x4b800000, v2
	v_cmp_gt_f32_e32 vcc, s91, v2
	s_waitcnt vmcnt(7)
	v_mov_b32_e32 v46, v64
	v_mov_b32_e32 v47, v65
	v_mov_b32_e32 v48, v66
	v_mov_b32_e32 v49, v67
	v_lshlrev_b32_e32 v4, 16, v51
	v_lshlrev_b32_e32 v14, 16, v50
	v_mul_f32_e32 v10, 0xbfb8aa3b, v4
	v_mul_f32_e32 v30, 0xbfb8aa3b, v14
	v_exp_f32_e32 v10, v10
	v_exp_f32_e32 v30, v30
	v_and_b32_e32 v5, 0xffff0000, v51
	v_and_b32_e32 v15, 0xffff0000, v50
	v_mul_f32_e32 v11, 0xbfb8aa3b, v5
	v_mul_f32_e32 v31, 0xbfb8aa3b, v15
	v_exp_f32_e32 v11, v11
	v_add_f32_e32 v10, 1.0, v10
	v_cndmask_b32_e32 v2, v2, v3, vcc
	v_exp_f32_e32 v50, v31
	v_add_f32_e32 v51, 1.0, v30
	v_rcp_f32_e32 v30, v10
	v_rsq_f32_e32 v10, v2
	v_add_f32_e32 v11, 1.0, v11
	v_rcp_f32_e32 v31, v11
	v_add_f32_e32 v3, 1.0, v50
	v_mul_f32_e32 v11, 0x45800000, v10
	v_rcp_f32_e32 v2, v51
	v_rcp_f32_e32 v3, v3
	v_cndmask_b32_e32 v10, v10, v11, vcc
	v_pk_mul_f32 v[50:51], v[56:57], v[10:11] op_sel_hi:[1,0]
	v_pk_mul_f32 v[42:43], v[42:43], v[10:11] op_sel_hi:[1,0]
	v_pk_mul_f32 v[46:47], v[46:47], v[50:51]
	s_nop 0
	v_pk_mul_f32 v[14:15], v[46:47], v[14:15]
	v_lshlrev_b32_e32 v46, 16, v40
	v_pk_mul_f32 v[2:3], v[2:3], v[14:15]
	v_pk_mul_f32 v[14:15], v[54:55], v[10:11] op_sel_hi:[1,0]
	v_cvt_pk_bf16_f32 v2, v2, v3
	v_pk_mul_f32 v[14:15], v[48:49], v[14:15]
	v_and_b32_e32 v47, 0xffff0000, v40
	v_pk_mul_f32 v[4:5], v[14:15], v[4:5]
	v_mul_f32_e32 v48, 0xbfb8aa3b, v47
	v_pk_mul_f32 v[4:5], v[30:31], v[4:5]
	v_pk_mul_f32 v[30:31], v[44:45], v[10:11] op_sel_hi:[1,0]
	v_cvt_pk_bf16_f32 v3, v4, v5
	global_store_dwordx2 v[34:35], v[2:3], off
	s_nop 0
	s_nop 0
	v_mov_b32_e32 v14, v244
	v_mov_b32_e32 v15, v245
	v_lshlrev_b32_e32 v44, 16, v41
	v_and_b32_e32 v45, 0xffff0000, v41
	v_mul_f32_e32 v11, 0xbfb8aa3b, v44
	v_mul_f32_e32 v40, 0xbfb8aa3b, v45
	v_mul_f32_e32 v41, 0xbfb8aa3b, v46
	v_exp_f32_e32 v11, v11
	v_exp_f32_e32 v40, v40
	v_exp_f32_e32 v41, v41
	v_exp_f32_e32 v48, v48
	v_add_f32_e32 v11, 1.0, v11
	v_add_f32_e32 v49, 1.0, v40
	v_add_f32_e32 v50, 1.0, v41
	v_add_f32_e32 v51, 1.0, v48
	v_rcp_f32_e32 v40, v11
	v_rcp_f32_e32 v41, v49
	v_rcp_f32_e32 v48, v50
	v_rcp_f32_e32 v49, v51
	v_pk_mul_f32 v[38:39], v[38:39], v[10:11] op_sel_hi:[1,0]
	v_pk_mul_f32 v[28:29], v[28:29], v[10:11] op_sel_hi:[1,0]
	s_waitcnt vmcnt(7)
; __device__ __forceinline__ float bflo(unsigned u) { return __uint_as_float(u << 16); }
; __device__ __forceinline__ float bfhi(unsigned u) { return __uint_as_float(u & 0xffff0000u); }
; DI float bflo(unsigned u) { return __uint_as_float(u << 16); }
; DI float bfhi(unsigned u) { return __uint_as_float(u & 0xffff0000u); }
; DI unsigned pk2(float lo, float hi) { f32x2_t v = {lo, hi}; bf16x2_t b = __builtin_convertvector(v, bf16x2_t); return __builtin_bit_cast(unsigned, b); }
; DI float sigmf(float v) { return __builtin_amdgcn_rcpf(1.0f + __expf(-v)); }
; DI void fox_attn_blk(const Params& P, unsigned char* lds, LAS unsigned char* ldsl, int tid, int G, float PRUNE, int pir) {
;     ...
; #pragma unroll
;         for (int blk = 0; blk < 2; ++blk)
; #pragma unroll
;             for (int gi = 0; gi < 4; ++gi) { const int d = 32 * blk + 8 * gi + 4 * hi;
;                 const u32x2 z = *(const u32x2*)(FZ + rowoff + d); const f32x4 w = *(const f32x4*)(P.in[11] + d);
;                 const float z0 = bflo(z.x), z1 = bfhi(z.x), z2 = bflo(z.y), z3 = bfhi(z.y);
;                 u32x2 o; o.x = pk2(oT[blk][4 * gi] * rstd * w.x * z0 * sigmf(z0), oT[blk][4 * gi + 1] * rstd * w.y * z1 * sigmf(z1));
;                 o.y = pk2(oT[blk][4 * gi + 2] * rstd * w.z * z2 * sigmf(z2), oT[blk][4 * gi + 3] * rstd * w.w * z3 * sigmf(z3));
;                 *(u32x2*)(YB + rowoff + d) = o; }
	v_mov_b32_e32 v2, v68
	v_mov_b32_e32 v3, v69
	v_mov_b32_e32 v4, v70
	v_mov_b32_e32 v5, v71
	v_pk_mul_f32 v[2:3], v[2:3], v[30:31]
	v_pk_mul_f32 v[4:5], v[4:5], v[42:43]
	v_pk_mul_f32 v[2:3], v[2:3], v[46:47]
	v_pk_mul_f32 v[4:5], v[4:5], v[44:45]
	v_pk_mul_f32 v[2:3], v[48:49], v[2:3]
	v_pk_mul_f32 v[4:5], v[40:41], v[4:5]
	v_cvt_pk_bf16_f32 v2, v2, v3
	v_cvt_pk_bf16_f32 v3, v4, v5
	global_store_dwordx2 v[34:35], v[2:3], off offset:16
	s_nop 0
	s_nop 0
	v_mov_b32_e32 v30, v246
	v_mov_b32_e32 v31, v247
	v_lshlrev_b32_e32 v40, 16, v15
	v_and_b32_e32 v41, 0xffff0000, v15
	v_lshlrev_b32_e32 v42, 16, v14
	v_and_b32_e32 v43, 0xffff0000, v14
	v_mul_f32_e32 v11, 0xbfb8aa3b, v40
	v_mul_f32_e32 v14, 0xbfb8aa3b, v41
	v_mul_f32_e32 v15, 0xbfb8aa3b, v42
	v_mul_f32_e32 v44, 0xbfb8aa3b, v43
	v_exp_f32_e32 v11, v11
	v_exp_f32_e32 v14, v14
	v_exp_f32_e32 v15, v15
	v_exp_f32_e32 v44, v44
	v_add_f32_e32 v11, 1.0, v11
	v_add_f32_e32 v45, 1.0, v14
	v_add_f32_e32 v46, 1.0, v15
	v_add_f32_e32 v47, 1.0, v44
	v_rcp_f32_e32 v14, v11
	v_rcp_f32_e32 v15, v45
	v_rcp_f32_e32 v44, v46
	v_rcp_f32_e32 v45, v47
	v_pk_mul_f32 v[26:27], v[26:27], v[10:11] op_sel_hi:[1,0]
	s_waitcnt vmcnt(7)
	v_mov_b32_e32 v2, v72
	v_mov_b32_e32 v3, v73
	v_mov_b32_e32 v4, v74
	v_mov_b32_e32 v5, v75
	v_pk_mul_f32 v[2:3], v[2:3], v[38:39]
	v_pk_mul_f32 v[4:5], v[4:5], v[28:29]
	v_pk_mul_f32 v[2:3], v[2:3], v[42:43]
	v_pk_mul_f32 v[4:5], v[4:5], v[40:41]
	v_pk_mul_f32 v[2:3], v[2:3], v[44:45]
	v_pk_mul_f32 v[4:5], v[4:5], v[14:15]
	v_cvt_pk_bf16_f32 v2, v2, v3
	v_cvt_pk_bf16_f32 v3, v4, v5
	global_store_dwordx2 v[34:35], v[2:3], off offset:32
	s_nop 0
	s_nop 0
	v_mov_b32_e32 v14, v248
	v_mov_b32_e32 v15, v249
	v_pk_mul_f32 v[28:29], v[32:33], v[10:11] op_sel_hi:[1,0]
	v_lshlrev_b32_e32 v32, 16, v30
	v_and_b32_e32 v33, 0xffff0000, v30
	v_lshlrev_b32_e32 v30, 16, v31
	v_and_b32_e32 v31, 0xffff0000, v31
	v_mul_f32_e32 v11, 0xbfb8aa3b, v32
	v_mul_f32_e32 v38, 0xbfb8aa3b, v33
	v_mul_f32_e32 v39, 0xbfb8aa3b, v30
	v_mul_f32_e32 v40, 0xbfb8aa3b, v31
	v_exp_f32_e32 v11, v11
	v_exp_f32_e32 v38, v38
	v_exp_f32_e32 v39, v39
	v_exp_f32_e32 v40, v40
	v_add_f32_e32 v11, 1.0, v11
	v_add_f32_e32 v41, 1.0, v38
	v_add_f32_e32 v42, 1.0, v39
	v_add_f32_e32 v43, 1.0, v40
	v_rcp_f32_e32 v38, v11
	v_rcp_f32_e32 v39, v41
	v_rcp_f32_e32 v40, v42
	v_rcp_f32_e32 v41, v43
	v_pk_mul_f32 v[24:25], v[24:25], v[10:11] op_sel_hi:[1,0]
	v_pk_mul_f32 v[22:23], v[22:23], v[10:11] op_sel_hi:[1,0]
	s_waitcnt vmcnt(7)
	v_mov_b32_e32 v2, v76
	v_mov_b32_e32 v3, v77
	v_mov_b32_e32 v4, v78
	v_mov_b32_e32 v5, v79
	v_pk_mul_f32 v[2:3], v[26:27], v[2:3]
	v_pk_mul_f32 v[4:5], v[28:29], v[4:5]
	v_pk_mul_f32 v[2:3], v[2:3], v[32:33]
	v_pk_mul_f32 v[4:5], v[4:5], v[30:31]
	v_pk_mul_f32 v[2:3], v[2:3], v[38:39]
	v_pk_mul_f32 v[4:5], v[4:5], v[40:41]
	v_cvt_pk_bf16_f32 v2, v2, v3
	v_cvt_pk_bf16_f32 v3, v4, v5
	global_store_dwordx2 v[34:35], v[2:3], off offset:48
	s_nop 0
	s_nop 0
	v_mov_b32_e32 v26, v250
	v_mov_b32_e32 v27, v251
	v_lshlrev_b32_e32 v28, 16, v15
	v_and_b32_e32 v29, 0xffff0000, v15
	v_lshlrev_b32_e32 v30, 16, v14
	v_and_b32_e32 v31, 0xffff0000, v14
	v_mul_f32_e32 v11, 0xbfb8aa3b, v28
	v_mul_f32_e32 v14, 0xbfb8aa3b, v29
	v_mul_f32_e32 v15, 0xbfb8aa3b, v30
	v_mul_f32_e32 v32, 0xbfb8aa3b, v31
	v_exp_f32_e32 v11, v11
	v_exp_f32_e32 v14, v14
	v_exp_f32_e32 v15, v15
	v_exp_f32_e32 v32, v32
	v_add_f32_e32 v11, 1.0, v11
	v_add_f32_e32 v33, 1.0, v14
	v_add_f32_e32 v38, 1.0, v15
	v_add_f32_e32 v39, 1.0, v32
	v_rcp_f32_e32 v14, v11
	v_rcp_f32_e32 v15, v33
	v_rcp_f32_e32 v32, v38
	v_rcp_f32_e32 v33, v39
	v_pk_mul_f32 v[20:21], v[20:21], v[10:11] op_sel_hi:[1,0]
	v_pk_mul_f32 v[18:19], v[18:19], v[10:11] op_sel_hi:[1,0]
	s_waitcnt vmcnt(7)
; __device__ __forceinline__ float bflo(unsigned u) { return __uint_as_float(u << 16); }
; __device__ __forceinline__ float bfhi(unsigned u) { return __uint_as_float(u & 0xffff0000u); }
; DI float bflo(unsigned u) { return __uint_as_float(u << 16); }
; DI float bfhi(unsigned u) { return __uint_as_float(u & 0xffff0000u); }
; DI unsigned pk2(float lo, float hi) { f32x2_t v = {lo, hi}; bf16x2_t b = __builtin_convertvector(v, bf16x2_t); return __builtin_bit_cast(unsigned, b); }
; DI float sigmf(float v) { return __builtin_amdgcn_rcpf(1.0f + __expf(-v)); }
; DI void fox_attn_blk(const Params& P, unsigned char* lds, LAS unsigned char* ldsl, int tid, int G, float PRUNE, int pir) {
;     ...
; #pragma unroll
;         for (int blk = 0; blk < 2; ++blk)
; #pragma unroll
;             for (int gi = 0; gi < 4; ++gi) { const int d = 32 * blk + 8 * gi + 4 * hi;
;                 const u32x2 z = *(const u32x2*)(FZ + rowoff + d); const f32x4 w = *(const f32x4*)(P.in[11] + d);
;                 const float z0 = bflo(z.x), z1 = bfhi(z.x), z2 = bflo(z.y), z3 = bfhi(z.y);
;                 u32x2 o; o.x = pk2(oT[blk][4 * gi] * rstd * w.x * z0 * sigmf(z0), oT[blk][4 * gi + 1] * rstd * w.y * z1 * sigmf(z1));
;                 o.y = pk2(oT[blk][4 * gi + 2] * rstd * w.z * z2 * sigmf(z2), oT[blk][4 * gi + 3] * rstd * w.w * z3 * sigmf(z3));
;                 *(u32x2*)(YB + rowoff + d) = o; }
	v_mov_b32_e32 v2, v80
	v_mov_b32_e32 v3, v81
	v_mov_b32_e32 v4, v82
	v_mov_b32_e32 v5, v83
	v_pk_mul_f32 v[2:3], v[24:25], v[2:3]
	v_pk_mul_f32 v[4:5], v[22:23], v[4:5]
	v_pk_mul_f32 v[2:3], v[2:3], v[30:31]
	v_pk_mul_f32 v[4:5], v[4:5], v[28:29]
	v_pk_mul_f32 v[2:3], v[2:3], v[32:33]
	v_pk_mul_f32 v[4:5], v[4:5], v[14:15]
	v_cvt_pk_bf16_f32 v2, v2, v3
	v_cvt_pk_bf16_f32 v3, v4, v5
	global_store_dwordx2 v[34:35], v[2:3], off offset:64
	s_nop 0
	s_nop 0
	v_mov_b32_e32 v14, v252
	v_mov_b32_e32 v15, v253
	v_lshlrev_b32_e32 v22, 16, v27
	v_and_b32_e32 v23, 0xffff0000, v27
	v_lshlrev_b32_e32 v24, 16, v26
	v_and_b32_e32 v25, 0xffff0000, v26
	v_mul_f32_e32 v11, 0xbfb8aa3b, v22
	v_mul_f32_e32 v26, 0xbfb8aa3b, v23
	v_mul_f32_e32 v27, 0xbfb8aa3b, v24
	v_mul_f32_e32 v28, 0xbfb8aa3b, v25
	v_exp_f32_e32 v11, v11
	v_exp_f32_e32 v26, v26
	v_exp_f32_e32 v27, v27
	v_exp_f32_e32 v28, v28
	v_add_f32_e32 v11, 1.0, v11
	v_add_f32_e32 v29, 1.0, v26
	v_add_f32_e32 v30, 1.0, v27
	v_add_f32_e32 v31, 1.0, v28
	v_rcp_f32_e32 v26, v11
	v_rcp_f32_e32 v27, v29
	v_rcp_f32_e32 v28, v30
	v_rcp_f32_e32 v29, v31
	v_pk_mul_f32 v[12:13], v[12:13], v[10:11] op_sel_hi:[1,0]
	v_pk_mul_f32 v[8:9], v[8:9], v[10:11] op_sel_hi:[1,0]
	s_waitcnt vmcnt(7)
	v_mov_b32_e32 v2, v84
	v_mov_b32_e32 v3, v85
	v_mov_b32_e32 v4, v86
	v_mov_b32_e32 v5, v87
	v_pk_mul_f32 v[2:3], v[20:21], v[2:3]
	v_pk_mul_f32 v[4:5], v[18:19], v[4:5]
	v_pk_mul_f32 v[2:3], v[2:3], v[24:25]
	v_pk_mul_f32 v[4:5], v[4:5], v[22:23]
	v_pk_mul_f32 v[2:3], v[2:3], v[28:29]
	v_pk_mul_f32 v[4:5], v[4:5], v[26:27]
	v_cvt_pk_bf16_f32 v2, v2, v3
	v_cvt_pk_bf16_f32 v3, v4, v5
	global_store_dwordx2 v[34:35], v[2:3], off offset:80
	s_nop 0
	s_nop 0
	v_mov_b32_e32 v18, v254
	v_mov_b32_e32 v19, v255
	v_lshlrev_b32_e32 v20, 16, v15
	v_and_b32_e32 v21, 0xffff0000, v15
	v_lshlrev_b32_e32 v22, 16, v14
	v_and_b32_e32 v23, 0xffff0000, v14
	v_mul_f32_e32 v11, 0xbfb8aa3b, v20
	v_mul_f32_e32 v14, 0xbfb8aa3b, v21
	v_mul_f32_e32 v15, 0xbfb8aa3b, v22
	v_mul_f32_e32 v24, 0xbfb8aa3b, v23
	v_exp_f32_e32 v11, v11
	v_exp_f32_e32 v14, v14
	v_exp_f32_e32 v15, v15
	v_exp_f32_e32 v24, v24
	v_add_f32_e32 v11, 1.0, v11
	v_add_f32_e32 v25, 1.0, v14
	v_add_f32_e32 v26, 1.0, v15
	v_add_f32_e32 v27, 1.0, v24
	v_rcp_f32_e32 v14, v11
	v_rcp_f32_e32 v15, v25
	v_rcp_f32_e32 v24, v26
	v_rcp_f32_e32 v25, v27
	v_pk_mul_f32 v[6:7], v[6:7], v[10:11] op_sel_hi:[1,0]
	s_waitcnt vmcnt(7)
	v_mov_b32_e32 v2, v88
	v_mov_b32_e32 v3, v89
	v_mov_b32_e32 v4, v90
	v_mov_b32_e32 v5, v91
	v_pk_mul_f32 v[2:3], v[12:13], v[2:3]
	v_pk_mul_f32 v[4:5], v[8:9], v[4:5]
	v_pk_mul_f32 v[2:3], v[2:3], v[22:23]
	v_pk_mul_f32 v[4:5], v[4:5], v[20:21]
	v_pk_mul_f32 v[2:3], v[2:3], v[24:25]
	v_pk_mul_f32 v[4:5], v[4:5], v[14:15]
	v_cvt_pk_bf16_f32 v2, v2, v3
	v_cvt_pk_bf16_f32 v3, v4, v5
	global_store_dwordx2 v[34:35], v[2:3], off offset:96
	s_nop 0
	v_lshlrev_b32_e32 v8, 16, v18
	v_and_b32_e32 v9, 0xffff0000, v18
	v_lshlrev_b32_e32 v15, 16, v19
	v_mul_f32_e32 v11, 0xbfb8aa3b, v8
	v_mul_f32_e32 v12, 0xbfb8aa3b, v9
	v_mul_f32_e32 v14, v16, v10
	v_mul_f32_e32 v13, 0xbfb8aa3b, v15
	v_exp_f32_e32 v16, v11
	v_exp_f32_e32 v12, v12
	v_exp_f32_e32 v13, v13
	v_mov_b32_e32 v11, v10
	v_add_f32_e32 v10, 1.0, v16
	v_add_f32_e32 v16, 1.0, v12
	v_add_f32_e32 v18, 1.0, v13
	v_rcp_f32_e32 v12, v10
	v_rcp_f32_e32 v13, v16
	v_rcp_f32_e32 v10, v18
	s_waitcnt vmcnt(7)
	v_mov_b32_e32 v2, v96
	v_mov_b32_e32 v3, v97
	v_mov_b32_e32 v4, v98
	v_mov_b32_e32 v5, v99
	v_pk_mul_f32 v[2:3], v[6:7], v[2:3]
	v_mul_f32_e32 v4, v14, v4
	v_pk_mul_f32 v[2:3], v[2:3], v[8:9]
	v_mul_f32_e32 v16, v4, v15
	v_pk_mul_f32 v[2:3], v[2:3], v[12:13]
	v_pk_mul_f32 v[6:7], v[16:17], v[10:11]
	v_cvt_pk_bf16_f32 v2, v2, v3
